# v64 + grid barriers: non-leader workgroups poll the top-level release generation directly (one atomic + one poll hop less)
# speedup vs baseline: 1.3138x; 1.3138x over previous
; __device__ __forceinline__ unsigned xb_ld(unsigned* p)              { return __hip_atomic_load(p, __ATOMIC_RELAXED, __HIP_MEMORY_SCOPE_AGENT); }
; __device__ __forceinline__ unsigned xb_add(unsigned* p, unsigned v) { return __hip_atomic_fetch_add(p, v, __ATOMIC_RELAXED, __HIP_MEMORY_SCOPE_AGENT); }
; #define XB_SPIN(cond, bar) do { unsigned _sp = 0; while (cond) { __builtin_amdgcn_s_sleep(1); \
;     if ((++_sp & 255u) == 0u) { if (xb_ld(&(bar)[XB_TMO])) break; if (_sp > XB_SPIN_CAP) { atomicAdd(&(bar)[XB_TMO], 1u); break; } } } } while (0)
; __device__ __forceinline__ void xcd_barrier(const XcdBarrier& b) {
;     ...
;         const unsigned old = xb_add(&bar[XB_XSUB(b.x)], 1u);
;         const unsigned gen = old / nloc;
;         if (old + 1u == (gen + 1u) * nloc) {
;             __builtin_amdgcn_fence(__ATOMIC_RELEASE, "agent");
;             asm volatile("s_waitcnt vmcnt(0)" ::: "memory");
;             const unsigned og = xb_add(&bar[XB_TOP], 1u);
;             const unsigned tg = og / nx;
;             if (og + 1u == (tg + 1u) * nx) xb_add(&bar[XB_TOPGEN], 1u);
;             else XB_SPIN(xb_ld(&bar[XB_TOPGEN]) == tg, bar);
;             __builtin_amdgcn_fence(__ATOMIC_ACQUIRE, "agent");
;             xb_add(&bar[XB_XGEN(b.x)], 1u);
;             asm volatile("s_waitcnt vmcnt(0)" ::: "memory");
;         } else {
;             XB_SPIN(xb_ld(&bar[XB_XGEN(b.x)]) == gen, bar);
.LBB0_202:
	s_or_b64 exec, exec, s[8:9]
	v_cvt_f32_u32_e32 v4, v2
	s_waitcnt vmcnt(0)
	v_readfirstlane_b32 s3, v3
	v_sub_u32_e32 v3, 0, v2
	v_rcp_iflag_f32_e32 v4, v4
	v_add_u32_e32 v5, s3, v1
	v_mul_f32_e32 v4, 0x4f7ffffe, v4
	v_cvt_u32_f32_e32 v4, v4
	v_mul_lo_u32 v1, v3, v4
	v_mul_hi_u32 v1, v4, v1
	v_add_u32_e32 v1, v4, v1
	v_mul_hi_u32 v1, v5, v1
	v_mul_lo_u32 v3, v1, v2
	v_sub_u32_e32 v3, v5, v3
	v_add_u32_e32 v4, 1, v1
	v_cmp_ge_u32_e32 vcc, v3, v2
	s_nop 1
	v_cndmask_b32_e32 v1, v1, v4, vcc
	v_sub_u32_e32 v4, v3, v2
	v_cndmask_b32_e32 v3, v3, v4, vcc
	v_add_u32_e32 v4, 1, v1
	v_cmp_ge_u32_e32 vcc, v3, v2
	v_add_u32_e32 v3, 1, v5
	s_nop 0
	v_cndmask_b32_e32 v1, v1, v4, vcc
	v_mul_lo_u32 v4, v2, v1
	v_add_u32_e32 v2, v4, v2
	v_cmp_ne_u32_e32 vcc, v3, v2
	s_and_saveexec_b64 s[6:7], vcc
	s_xor_b64 s[6:7], exec, s[6:7]
	s_cbranch_execz .LBB0_216
	s_waitcnt lgkmcnt(0)
	v_mov_b32_e32 v0, 0x3100
	global_load_dword v0, v0, s[84:85] offset:1024 sc1
	s_add_u32 s14, s84, 0x3500
	s_addc_u32 s15, s85, 0
	s_waitcnt vmcnt(0)
	v_cmp_eq_u32_e32 vcc, v0, v1
	s_and_saveexec_b64 s[8:9], vcc
	s_cbranch_execz .LBB0_215
	s_add_u32 s10, s82, 0x38a00200
	s_addc_u32 s11, s83, 0
	s_mov_b32 s3, 1
	s_mov_b64 s[16:17], 0
	v_mov_b32_e32 v0, 0
	s_branch .LBB0_206

; __device__ __forceinline__ unsigned xb_ld(unsigned* p)              { return __hip_atomic_load(p, __ATOMIC_RELAXED, __HIP_MEMORY_SCOPE_AGENT); }
; __device__ __forceinline__ unsigned xb_add(unsigned* p, unsigned v) { return __hip_atomic_fetch_add(p, v, __ATOMIC_RELAXED, __HIP_MEMORY_SCOPE_AGENT); }
; #define XB_SPIN(cond, bar) do { unsigned _sp = 0; while (cond) { __builtin_amdgcn_s_sleep(1); \
;     if ((++_sp & 255u) == 0u) { if (xb_ld(&(bar)[XB_TMO])) break; if (_sp > XB_SPIN_CAP) { atomicAdd(&(bar)[XB_TMO], 1u); break; } } } } while (0)
; __device__ __forceinline__ void xcd_barrier(const XcdBarrier& b) {
;     ...
;         const unsigned old = xb_add(&bar[XB_XSUB(b.x)], 1u);
;         const unsigned gen = old / nloc;
;         if (old + 1u == (gen + 1u) * nloc) {
;             __builtin_amdgcn_fence(__ATOMIC_RELEASE, "agent");
;             asm volatile("s_waitcnt vmcnt(0)" ::: "memory");
;             const unsigned og = xb_add(&bar[XB_TOP], 1u);
;             const unsigned tg = og / nx;
;             if (og + 1u == (tg + 1u) * nx) xb_add(&bar[XB_TOPGEN], 1u);
;             else XB_SPIN(xb_ld(&bar[XB_TOPGEN]) == tg, bar);
;             __builtin_amdgcn_fence(__ATOMIC_ACQUIRE, "agent");
;             xb_add(&bar[XB_XGEN(b.x)], 1u);
;             asm volatile("s_waitcnt vmcnt(0)" ::: "memory");
;         } else {
;             XB_SPIN(xb_ld(&bar[XB_XGEN(b.x)]) == gen, bar);
.LBB0_431:
	s_or_b64 exec, exec, s[10:11]
	v_cvt_f32_u32_e32 v4, v2
	s_waitcnt vmcnt(0)
	v_readfirstlane_b32 s3, v3
	v_sub_u32_e32 v3, 0, v2
	v_rcp_iflag_f32_e32 v4, v4
	v_add_u32_e32 v5, s3, v1
	v_mul_f32_e32 v4, 0x4f7ffffe, v4
	v_cvt_u32_f32_e32 v4, v4
	v_mul_lo_u32 v1, v3, v4
	v_mul_hi_u32 v1, v4, v1
	v_add_u32_e32 v1, v4, v1
	v_mul_hi_u32 v1, v5, v1
	v_mul_lo_u32 v3, v1, v2
	v_sub_u32_e32 v3, v5, v3
	v_add_u32_e32 v4, 1, v1
	v_cmp_ge_u32_e32 vcc, v3, v2
	s_nop 1
	v_cndmask_b32_e32 v1, v1, v4, vcc
	v_sub_u32_e32 v4, v3, v2
	v_cndmask_b32_e32 v3, v3, v4, vcc
	v_add_u32_e32 v4, 1, v1
	v_cmp_ge_u32_e32 vcc, v3, v2
	v_add_u32_e32 v3, 1, v5
	s_nop 0
	v_cndmask_b32_e32 v1, v1, v4, vcc
	v_mul_lo_u32 v4, v2, v1
	v_add_u32_e32 v2, v4, v2
	v_cmp_ne_u32_e32 vcc, v3, v2
	s_and_saveexec_b64 s[8:9], vcc
	s_xor_b64 s[8:9], exec, s[8:9]
	s_cbranch_execz .LBB0_445
	s_waitcnt lgkmcnt(0)
	v_mov_b32_e32 v0, 0x3100
	global_load_dword v0, v0, s[84:85] offset:1024 sc1
	s_add_u32 s14, s84, 0x3500
	s_addc_u32 s15, s85, 0
	s_waitcnt vmcnt(0)
	v_cmp_eq_u32_e32 vcc, v0, v1
	s_and_saveexec_b64 s[10:11], vcc
	s_cbranch_execz .LBB0_444
	s_add_u32 s12, s82, 0x38a00200
	s_addc_u32 s13, s83, 0
	s_mov_b32 s3, 1
	s_mov_b64 s[16:17], 0
	v_mov_b32_e32 v0, 0
	s_branch .LBB0_435

; __device__ __forceinline__ unsigned xb_ld(unsigned* p)              { return __hip_atomic_load(p, __ATOMIC_RELAXED, __HIP_MEMORY_SCOPE_AGENT); }
; __device__ __forceinline__ unsigned xb_add(unsigned* p, unsigned v) { return __hip_atomic_fetch_add(p, v, __ATOMIC_RELAXED, __HIP_MEMORY_SCOPE_AGENT); }
; #define XB_SPIN(cond, bar) do { unsigned _sp = 0; while (cond) { __builtin_amdgcn_s_sleep(1); \
;     if ((++_sp & 255u) == 0u) { if (xb_ld(&(bar)[XB_TMO])) break; if (_sp > XB_SPIN_CAP) { atomicAdd(&(bar)[XB_TMO], 1u); break; } } } } while (0)
; __device__ __forceinline__ void xcd_barrier(const XcdBarrier& b) {
;     ...
;         const unsigned old = xb_add(&bar[XB_XSUB(b.x)], 1u);
;         const unsigned gen = old / nloc;
;         if (old + 1u == (gen + 1u) * nloc) {
;             __builtin_amdgcn_fence(__ATOMIC_RELEASE, "agent");
;             asm volatile("s_waitcnt vmcnt(0)" ::: "memory");
;             const unsigned og = xb_add(&bar[XB_TOP], 1u);
;             const unsigned tg = og / nx;
;             if (og + 1u == (tg + 1u) * nx) xb_add(&bar[XB_TOPGEN], 1u);
;             else XB_SPIN(xb_ld(&bar[XB_TOPGEN]) == tg, bar);
;             __builtin_amdgcn_fence(__ATOMIC_ACQUIRE, "agent");
;             xb_add(&bar[XB_XGEN(b.x)], 1u);
;             asm volatile("s_waitcnt vmcnt(0)" ::: "memory");
;         } else {
;             XB_SPIN(xb_ld(&bar[XB_XGEN(b.x)]) == gen, bar);
.LBB0_567:
	s_or_b64 exec, exec, s[8:9]
	v_cvt_f32_u32_e32 v4, v2
	s_waitcnt vmcnt(0)
	v_readfirstlane_b32 s3, v3
	v_sub_u32_e32 v3, 0, v2
	v_rcp_iflag_f32_e32 v4, v4
	v_add_u32_e32 v5, s3, v1
	v_mul_f32_e32 v4, 0x4f7ffffe, v4
	v_cvt_u32_f32_e32 v4, v4
	v_mul_lo_u32 v1, v3, v4
	v_mul_hi_u32 v1, v4, v1
	v_add_u32_e32 v1, v4, v1
	v_mul_hi_u32 v1, v5, v1
	v_mul_lo_u32 v3, v1, v2
	v_sub_u32_e32 v3, v5, v3
	v_add_u32_e32 v4, 1, v1
	v_cmp_ge_u32_e32 vcc, v3, v2
	s_nop 1
	v_cndmask_b32_e32 v1, v1, v4, vcc
	v_sub_u32_e32 v4, v3, v2
	v_cndmask_b32_e32 v3, v3, v4, vcc
	v_add_u32_e32 v4, 1, v1
	v_cmp_ge_u32_e32 vcc, v3, v2
	v_add_u32_e32 v3, 1, v5
	s_nop 0
	v_cndmask_b32_e32 v1, v1, v4, vcc
	v_mul_lo_u32 v4, v2, v1
	v_add_u32_e32 v2, v4, v2
	v_cmp_ne_u32_e32 vcc, v3, v2
	s_and_saveexec_b64 s[6:7], vcc
	s_xor_b64 s[6:7], exec, s[6:7]
	s_cbranch_execz .LBB0_581
	s_waitcnt lgkmcnt(0)
	v_mov_b32_e32 v0, 0x3100
	global_load_dword v0, v0, s[84:85] offset:1024 sc1
	s_add_u32 s12, s84, 0x3500
	s_addc_u32 s13, s85, 0
	s_waitcnt vmcnt(0)
	v_cmp_eq_u32_e32 vcc, v0, v1
	s_and_saveexec_b64 s[8:9], vcc
	s_cbranch_execz .LBB0_580
	s_add_u32 s10, s66, 0x38a00200
	s_addc_u32 s11, s67, 0
	s_mov_b32 s3, 1
	s_mov_b64 s[14:15], 0
	v_mov_b32_e32 v0, 0
	s_branch .LBB0_571

; __device__ __forceinline__ unsigned xb_ld(unsigned* p)              { return __hip_atomic_load(p, __ATOMIC_RELAXED, __HIP_MEMORY_SCOPE_AGENT); }
; __device__ __forceinline__ unsigned xb_add(unsigned* p, unsigned v) { return __hip_atomic_fetch_add(p, v, __ATOMIC_RELAXED, __HIP_MEMORY_SCOPE_AGENT); }
; #define XB_SPIN(cond, bar) do { unsigned _sp = 0; while (cond) { __builtin_amdgcn_s_sleep(1); \
;     if ((++_sp & 255u) == 0u) { if (xb_ld(&(bar)[XB_TMO])) break; if (_sp > XB_SPIN_CAP) { atomicAdd(&(bar)[XB_TMO], 1u); break; } } } } while (0)
; __device__ __forceinline__ void xcd_barrier(const XcdBarrier& b) {
;     ...
;         const unsigned old = xb_add(&bar[XB_XSUB(b.x)], 1u);
;         const unsigned gen = old / nloc;
;         if (old + 1u == (gen + 1u) * nloc) {
;             __builtin_amdgcn_fence(__ATOMIC_RELEASE, "agent");
;             asm volatile("s_waitcnt vmcnt(0)" ::: "memory");
;             const unsigned og = xb_add(&bar[XB_TOP], 1u);
;             const unsigned tg = og / nx;
;             if (og + 1u == (tg + 1u) * nx) xb_add(&bar[XB_TOPGEN], 1u);
;             else XB_SPIN(xb_ld(&bar[XB_TOPGEN]) == tg, bar);
;             __builtin_amdgcn_fence(__ATOMIC_ACQUIRE, "agent");
;             xb_add(&bar[XB_XGEN(b.x)], 1u);
;             asm volatile("s_waitcnt vmcnt(0)" ::: "memory");
;         } else {
;             XB_SPIN(xb_ld(&bar[XB_XGEN(b.x)]) == gen, bar);
.LBB0_626:
	s_or_b64 exec, exec, s[10:11]
	v_cvt_f32_u32_e32 v4, v2
	s_waitcnt vmcnt(0)
	v_readfirstlane_b32 s3, v3
	v_sub_u32_e32 v3, 0, v2
	v_rcp_iflag_f32_e32 v4, v4
	v_add_u32_e32 v5, s3, v1
	v_mul_f32_e32 v4, 0x4f7ffffe, v4
	v_cvt_u32_f32_e32 v4, v4
	v_mul_lo_u32 v1, v3, v4
	v_mul_hi_u32 v1, v4, v1
	v_add_u32_e32 v1, v4, v1
	v_mul_hi_u32 v1, v5, v1
	v_mul_lo_u32 v3, v1, v2
	v_sub_u32_e32 v3, v5, v3
	v_add_u32_e32 v4, 1, v1
	v_cmp_ge_u32_e32 vcc, v3, v2
	s_nop 1
	v_cndmask_b32_e32 v1, v1, v4, vcc
	v_sub_u32_e32 v4, v3, v2
	v_cndmask_b32_e32 v3, v3, v4, vcc
	v_add_u32_e32 v4, 1, v1
	v_cmp_ge_u32_e32 vcc, v3, v2
	v_add_u32_e32 v3, 1, v5
	s_nop 0
	v_cndmask_b32_e32 v1, v1, v4, vcc
	v_mul_lo_u32 v4, v2, v1
	v_add_u32_e32 v2, v4, v2
	v_cmp_ne_u32_e32 vcc, v3, v2
	s_and_saveexec_b64 s[8:9], vcc
	s_xor_b64 s[8:9], exec, s[8:9]
	s_cbranch_execz .LBB0_640
	s_waitcnt lgkmcnt(0)
	v_mov_b32_e32 v0, 0x3100
	global_load_dword v0, v0, s[84:85] offset:1024 sc1
	s_add_u32 s14, s84, 0x3500
	s_addc_u32 s15, s85, 0
	s_waitcnt vmcnt(0)
	v_cmp_eq_u32_e32 vcc, v0, v1
	s_and_saveexec_b64 s[10:11], vcc
	s_cbranch_execz .LBB0_639
	s_add_u32 s12, s66, 0x38a00200
	s_addc_u32 s13, s67, 0
	s_mov_b32 s3, 1
	s_mov_b64 s[16:17], 0
	v_mov_b32_e32 v0, 0
	s_branch .LBB0_630

; __device__ __forceinline__ unsigned xb_ld(unsigned* p)              { return __hip_atomic_load(p, __ATOMIC_RELAXED, __HIP_MEMORY_SCOPE_AGENT); }
; __device__ __forceinline__ unsigned xb_add(unsigned* p, unsigned v) { return __hip_atomic_fetch_add(p, v, __ATOMIC_RELAXED, __HIP_MEMORY_SCOPE_AGENT); }
; #define XB_SPIN(cond, bar) do { unsigned _sp = 0; while (cond) { __builtin_amdgcn_s_sleep(1); \
;     if ((++_sp & 255u) == 0u) { if (xb_ld(&(bar)[XB_TMO])) break; if (_sp > XB_SPIN_CAP) { atomicAdd(&(bar)[XB_TMO], 1u); break; } } } } while (0)
; __device__ __forceinline__ void xcd_barrier(const XcdBarrier& b) {
;     ...
;         const unsigned old = xb_add(&bar[XB_XSUB(b.x)], 1u);
;         const unsigned gen = old / nloc;
;         if (old + 1u == (gen + 1u) * nloc) {
;             __builtin_amdgcn_fence(__ATOMIC_RELEASE, "agent");
;             asm volatile("s_waitcnt vmcnt(0)" ::: "memory");
;             const unsigned og = xb_add(&bar[XB_TOP], 1u);
;             const unsigned tg = og / nx;
;             if (og + 1u == (tg + 1u) * nx) xb_add(&bar[XB_TOPGEN], 1u);
;             else XB_SPIN(xb_ld(&bar[XB_TOPGEN]) == tg, bar);
;             __builtin_amdgcn_fence(__ATOMIC_ACQUIRE, "agent");
;             xb_add(&bar[XB_XGEN(b.x)], 1u);
;             asm volatile("s_waitcnt vmcnt(0)" ::: "memory");
;         } else {
;             XB_SPIN(xb_ld(&bar[XB_XGEN(b.x)]) == gen, bar);
.LBB0_1105:
	s_or_b64 exec, exec, s[20:21]
	v_cvt_f32_u32_e32 v4, v2
	s_waitcnt vmcnt(0)
	v_readfirstlane_b32 s3, v3
	v_sub_u32_e32 v3, 0, v2
	v_rcp_iflag_f32_e32 v4, v4
	v_add_u32_e32 v5, s3, v1
	v_mul_f32_e32 v4, 0x4f7ffffe, v4
	v_cvt_u32_f32_e32 v4, v4
	v_mul_lo_u32 v1, v3, v4
	v_mul_hi_u32 v1, v4, v1
	v_add_u32_e32 v1, v4, v1
	v_mul_hi_u32 v1, v5, v1
	v_mul_lo_u32 v3, v1, v2
	v_sub_u32_e32 v3, v5, v3
	v_add_u32_e32 v4, 1, v1
	v_cmp_ge_u32_e32 vcc, v3, v2
	s_nop 1
	v_cndmask_b32_e32 v1, v1, v4, vcc
	v_sub_u32_e32 v4, v3, v2
	v_cndmask_b32_e32 v3, v3, v4, vcc
	v_add_u32_e32 v4, 1, v1
	v_cmp_ge_u32_e32 vcc, v3, v2
	v_add_u32_e32 v3, 1, v5
	s_nop 0
	v_cndmask_b32_e32 v1, v1, v4, vcc
	v_mul_lo_u32 v4, v2, v1
	v_add_u32_e32 v2, v4, v2
	v_cmp_ne_u32_e32 vcc, v3, v2
	s_and_saveexec_b64 s[8:9], vcc
	s_xor_b64 s[8:9], exec, s[8:9]
	s_cbranch_execz .LBB0_1119
	s_waitcnt lgkmcnt(0)
	v_mov_b32_e32 v0, 0x3100
	global_load_dword v0, v0, s[84:85] offset:1024 sc1
	s_add_u32 s24, s84, 0x3500
	s_addc_u32 s25, s85, 0
	s_waitcnt vmcnt(0)
	v_cmp_eq_u32_e32 vcc, v0, v1
	s_and_saveexec_b64 s[20:21], vcc
	s_cbranch_execz .LBB0_1118
	s_add_u32 s22, s66, 0x38a00200
	s_addc_u32 s23, s67, 0
	s_mov_b32 s3, 1
	s_mov_b64 s[26:27], 0
	v_mov_b32_e32 v0, 0
	s_branch .LBB0_1109

; __device__ __forceinline__ unsigned xb_ld(unsigned* p)              { return __hip_atomic_load(p, __ATOMIC_RELAXED, __HIP_MEMORY_SCOPE_AGENT); }
; __device__ __forceinline__ unsigned xb_add(unsigned* p, unsigned v) { return __hip_atomic_fetch_add(p, v, __ATOMIC_RELAXED, __HIP_MEMORY_SCOPE_AGENT); }
; #define XB_SPIN(cond, bar) do { unsigned _sp = 0; while (cond) { __builtin_amdgcn_s_sleep(1); \
;     if ((++_sp & 255u) == 0u) { if (xb_ld(&(bar)[XB_TMO])) break; if (_sp > XB_SPIN_CAP) { atomicAdd(&(bar)[XB_TMO], 1u); break; } } } } while (0)
; __device__ __forceinline__ void xcd_barrier(const XcdBarrier& b) {
;     ...
;         const unsigned old = xb_add(&bar[XB_XSUB(b.x)], 1u);
;         const unsigned gen = old / nloc;
;         if (old + 1u == (gen + 1u) * nloc) {
;             __builtin_amdgcn_fence(__ATOMIC_RELEASE, "agent");
;             asm volatile("s_waitcnt vmcnt(0)" ::: "memory");
;             const unsigned og = xb_add(&bar[XB_TOP], 1u);
;             const unsigned tg = og / nx;
;             if (og + 1u == (tg + 1u) * nx) xb_add(&bar[XB_TOPGEN], 1u);
;             else XB_SPIN(xb_ld(&bar[XB_TOPGEN]) == tg, bar);
;             __builtin_amdgcn_fence(__ATOMIC_ACQUIRE, "agent");
;             xb_add(&bar[XB_XGEN(b.x)], 1u);
;             asm volatile("s_waitcnt vmcnt(0)" ::: "memory");
;         } else {
;             XB_SPIN(xb_ld(&bar[XB_XGEN(b.x)]) == gen, bar);
.LBB0_1192:
	s_or_b64 exec, exec, s[8:9]
	v_cvt_f32_u32_e32 v4, v2
	s_waitcnt vmcnt(0)
	v_readfirstlane_b32 s3, v3
	v_sub_u32_e32 v3, 0, v2
	v_rcp_iflag_f32_e32 v4, v4
	v_add_u32_e32 v5, s3, v1
	v_mul_f32_e32 v4, 0x4f7ffffe, v4
	v_cvt_u32_f32_e32 v4, v4
	v_mul_lo_u32 v1, v3, v4
	v_mul_hi_u32 v1, v4, v1
	v_add_u32_e32 v1, v4, v1
	v_mul_hi_u32 v1, v5, v1
	v_mul_lo_u32 v3, v1, v2
	v_sub_u32_e32 v3, v5, v3
	v_add_u32_e32 v4, 1, v1
	v_cmp_ge_u32_e32 vcc, v3, v2
	s_nop 1
	v_cndmask_b32_e32 v1, v1, v4, vcc
	v_sub_u32_e32 v4, v3, v2
	v_cndmask_b32_e32 v3, v3, v4, vcc
	v_add_u32_e32 v4, 1, v1
	v_cmp_ge_u32_e32 vcc, v3, v2
	v_add_u32_e32 v3, 1, v5
	s_nop 0
	v_cndmask_b32_e32 v1, v1, v4, vcc
	v_mul_lo_u32 v4, v2, v1
	v_add_u32_e32 v2, v4, v2
	v_cmp_ne_u32_e32 vcc, v3, v2
	s_and_saveexec_b64 s[6:7], vcc
	s_xor_b64 s[6:7], exec, s[6:7]
	s_cbranch_execz .LBB0_1206
	s_waitcnt lgkmcnt(0)
	v_mov_b32_e32 v0, 0x38a03100
	global_load_dword v0, v0, s[66:67] offset:1024 sc1
	s_add_u32 s24, s66, 0x38a03500
	s_addc_u32 s25, s67, 0
	s_waitcnt vmcnt(0)
	v_cmp_eq_u32_e32 vcc, v0, v1
	s_and_saveexec_b64 s[8:9], vcc
	s_cbranch_execz .LBB0_1205
	s_add_u32 s22, s66, 0x38a00200
	s_addc_u32 s23, s67, 0
	s_mov_b32 s3, 1
	s_mov_b64 s[26:27], 0
	v_mov_b32_e32 v0, 0
	s_branch .LBB0_1196
